# priority placement: the softmax wave keeps its high priority through the LDS-DMA issue and drops to 0 only before the row-max tree (DA+MLA)
# speedup vs baseline: 1.0074x; 1.0036x over previous
.LBB0_601:
	s_and_b64 vcc, exec, s[2:3]
	s_barrier
	s_cbranch_vccnz .LBB0_603
	s_mov_b32 m0, s93
	s_add_i32 s0, s94, s12
	global_load_lds_dwordx4 v150, s[58:59]
	s_add_u32 s58, s58, 0x100000
	s_addc_u32 s59, s59, 0
	s_add_i32 m0, s0, 0xc000
	s_nop 0
	global_load_lds_dwordx4 v170, s[60:61]
	s_add_i32 m0, s0, 0xc400
	s_add_u32 vcc_lo, s60, s24
	s_addc_u32 vcc_hi, s61, s25
	s_add_u32 s60, s60, 0x100000
	s_addc_u32 s61, s61, 0
	s_cmpk_lt_i32 s95, 0x84
	s_cselect_b32 s1, 0, -1
	s_cselect_b32 s0, 0, 0xffd00000
	global_load_lds_dwordx4 v172, vcc
	v_lshl_add_u64 v[130:131], v[174:175], 0, s[0:1]
	s_add_i32 s0, s97, 0
	s_add_i32 m0, s0, 0x18800
	v_lshl_add_u64 v[174:175], v[174:175], 0, s[20:21]
	global_load_lds_dword v[130:131], off
	s_add_i32 s95, s95, 1

.LBB0_605:
	s_setprio 0
	v_max_f32_e32 v130, v99, v99
	v_max_f32_e32 v131, v98, v98
	v_max_f32_e32 v130, v131, v130
	v_max3_f32 v130, v130, v100, v101
	v_max3_f32 v130, v130, v102, v103
	v_max3_f32 v130, v130, v104, v105
	v_max3_f32 v130, v130, v106, v107
	v_max3_f32 v130, v130, v108, v109
	v_max3_f32 v130, v130, v110, v111
	v_max3_f32 v130, v130, v112, v113
	v_max3_f32 v130, v130, v82, v83
	v_max3_f32 v130, v130, v84, v85
	v_max3_f32 v130, v130, v86, v87
	v_max3_f32 v130, v130, v88, v89
	v_max3_f32 v130, v130, v90, v91
	v_max3_f32 v130, v130, v92, v93
	v_max3_f32 v130, v130, v94, v95
	v_max3_f32 v130, v130, v96, v97
	v_mov_b32_e32 v131, v130
	s_nop 1
	v_permlane32_swap_b32_e32 v130, v131
	v_max_f32_e32 v131, v131, v131
	v_max_f32_e32 v130, v130, v130
	v_max_f32_e32 v130, v130, v131
	v_cmp_ge_f32_e32 vcc, s76, v130
	s_cmp_eq_u64 vcc, exec
	v_mov_b32_e32 v194, 1.0
	s_cbranch_scc0 .LBB0_627
	v_cmp_gt_f32_e32 vcc, 1.0, v194
	s_cbranch_vccz .LBB0_610

.LBB0_614:
	s_and_b64 vcc, exec, s[2:3]
	s_barrier
	s_cbranch_vccnz .LBB0_616
	s_add_i32 m0, s92, 0xa000
	s_add_i32 s0, s94, s74
	global_load_lds_dwordx4 v150, s[58:59]
	s_add_u32 s58, s58, 0x100000
	s_addc_u32 s59, s59, 0
	s_add_i32 m0, s0, 0xc000
	s_nop 0
	global_load_lds_dwordx4 v170, s[60:61]
	s_add_i32 m0, s0, 0xc400
	s_add_u32 vcc_lo, s60, s24
	s_addc_u32 vcc_hi, s61, s25
	s_add_u32 s60, s60, 0x100000
	s_addc_u32 s61, s61, 0
	s_cmpk_lt_i32 s95, 0x84
	s_cselect_b32 s1, 0, -1
	s_cselect_b32 s0, 0, 0xffd00000
	global_load_lds_dwordx4 v172, vcc
	v_lshl_add_u64 v[130:131], v[174:175], 0, s[0:1]
	s_add_i32 s0, s97, 0
	s_add_i32 m0, s0, 0x18800
	v_lshl_add_u64 v[174:175], v[174:175], 0, s[20:21]
	global_load_lds_dword v[130:131], off
	s_add_i32 s95, s95, 1

.LBB0_618:
	s_setprio 0
	v_max_f32_e32 v130, v99, v99
	v_max_f32_e32 v131, v98, v98
	v_max_f32_e32 v130, v131, v130
	v_max3_f32 v130, v130, v100, v101
	v_max3_f32 v130, v130, v102, v103
	v_max3_f32 v130, v130, v104, v105
	v_max3_f32 v130, v130, v106, v107
	v_max3_f32 v130, v130, v108, v109
	v_max3_f32 v130, v130, v110, v111
	v_max3_f32 v130, v130, v112, v113
	v_max3_f32 v130, v130, v82, v83
	v_max3_f32 v130, v130, v84, v85
	v_max3_f32 v130, v130, v86, v87
	v_max3_f32 v130, v130, v88, v89
	v_max3_f32 v130, v130, v90, v91
	v_max3_f32 v130, v130, v92, v93
	v_max3_f32 v130, v130, v94, v95
	v_max3_f32 v130, v130, v96, v97
	v_mov_b32_e32 v131, v130
	s_nop 1
	v_permlane32_swap_b32_e32 v130, v131
	v_max_f32_e32 v131, v131, v131
	v_max_f32_e32 v130, v130, v130
	v_max_f32_e32 v130, v130, v131
	v_cmp_ge_f32_e32 vcc, s76, v130
	s_cmp_eq_u64 vcc, exec
	v_mov_b32_e32 v197, 1.0
	s_cbranch_scc0 .LBB0_628
	v_cmp_gt_f32_e32 vcc, 1.0, v197
	s_cbranch_vccz .LBB0_623

.LBB0_668:
	s_and_b64 vcc, exec, s[2:3]
	s_barrier
	s_cbranch_vccnz .LBB0_670
	s_mov_b32 m0, s89
	s_add_i32 s8, s89, s95
	global_load_lds_dwordx4 v134, s[52:53]
	s_mov_b32 m0, s91
	s_nop 0
	global_load_lds_dwordx4 v154, s[52:53]
	s_mov_b32 m0, s92
	s_add_u32 s52, s52, 0x40000
	s_addc_u32 s53, s53, 0
	global_load_lds_dwordx4 v144, s[54:55]
	s_add_i32 m0, s8, 0xc000
	s_add_u32 s54, s54, 0x100000
	s_addc_u32 s55, s55, 0
	global_load_lds_dwordx4 v142, s[48:49]
	s_add_i32 m0, s8, 0xc400
	s_nop 0
	global_load_lds_dwordx4 v152, s[48:49]
	s_add_u32 s48, s48, 0x40000
	s_addc_u32 s49, s49, 0

.LBB0_672:
	s_setprio 0
	v_max_f32_e32 v118, v83, v83
	v_max_f32_e32 v119, v82, v82
	v_max_f32_e32 v118, v119, v118
	v_max3_f32 v118, v118, v84, v85
	v_max3_f32 v118, v118, v86, v87
	v_max3_f32 v118, v118, v88, v89
	v_max3_f32 v118, v118, v90, v91
	v_max3_f32 v118, v118, v92, v93
	v_max3_f32 v118, v118, v94, v95
	v_max3_f32 v118, v118, v96, v97
	v_max3_f32 v118, v118, v66, v67
	v_max3_f32 v118, v118, v68, v69
	v_max3_f32 v118, v118, v70, v71
	v_max3_f32 v118, v118, v72, v73
	v_max3_f32 v118, v118, v74, v75
	v_max3_f32 v118, v118, v76, v77
	v_max3_f32 v118, v118, v78, v79
	v_max3_f32 v118, v118, v80, v81
	v_mov_b32_e32 v119, v118
	s_nop 1
	v_permlane32_swap_b32_e32 v118, v119
	v_max_f32_e32 v119, v119, v119
	v_max_f32_e32 v118, v118, v118
	v_max_f32_e32 v118, v118, v119
	v_max_f32_e32 v120, v186, v186
	v_sub_f32_e32 v119, v118, v186
	v_max_f32_e32 v118, v120, v118
	v_sub_f32_e32 v120, v186, v118
	v_exp_f32_e32 v120, v120
	v_cmp_ge_f32_e32 vcc, s80, v119
	s_cmp_eq_u64 vcc, exec
	s_cselect_b64 s[8:9], -1, 0
	v_cndmask_b32_e64 v201, v120, 1.0, s[8:9]
	v_cmp_gt_f32_e32 vcc, 1.0, v201
	s_cbranch_vccz .LBB0_676
	s_and_saveexec_b64 s[56:57], s[4:5]
	ds_write_b32 v157, v201 offset:128
	s_or_b64 exec, exec, s[56:57]
	s_waitcnt lgkmcnt(0)
	v_add_u32_e32 v119, s18, v156
	ds_read_b128 v[120:123], v119 offset:128
	ds_read_b128 v[124:127], v119 offset:160
	ds_read_b128 v[128:131], v119 offset:192
	ds_read_b128 v[202:205], v119 offset:224
	s_waitcnt lgkmcnt(0)
	v_pk_mul_f32 v[34:35], v[120:121], v[34:35]
	v_pk_mul_f32 v[36:37], v[36:37], v[122:123]
	v_pk_mul_f32 v[38:39], v[38:39], v[124:125]
	v_pk_mul_f32 v[40:41], v[40:41], v[126:127]
	v_pk_mul_f32 v[42:43], v[42:43], v[128:129]
	v_pk_mul_f32 v[44:45], v[44:45], v[130:131]
	v_pk_mul_f32 v[46:47], v[46:47], v[202:203]
	v_pk_mul_f32 v[62:63], v[62:63], v[202:203]
	v_pk_mul_f32 v[58:59], v[58:59], v[128:129]
	v_pk_mul_f32 v[54:55], v[54:55], v[124:125]
	v_pk_mul_f32 v[64:65], v[64:65], v[204:205]
	v_pk_mul_f32 v[60:61], v[60:61], v[130:131]
	v_pk_mul_f32 v[56:57], v[56:57], v[126:127]
	v_pk_mul_f32 v[52:53], v[52:53], v[122:123]
	v_pk_mul_f32 v[50:51], v[50:51], v[120:121]
	v_pk_mul_f32 v[48:49], v[48:49], v[204:205]
	v_pk_mul_f32 v[2:3], v[120:121], v[2:3]
	v_pk_mul_f32 v[4:5], v[4:5], v[122:123]
	v_pk_mul_f32 v[6:7], v[6:7], v[124:125]
	v_pk_mul_f32 v[8:9], v[8:9], v[126:127]
	v_pk_mul_f32 v[10:11], v[10:11], v[128:129]
	v_pk_mul_f32 v[12:13], v[12:13], v[130:131]
	v_pk_mul_f32 v[14:15], v[14:15], v[202:203]
	v_pk_mul_f32 v[30:31], v[30:31], v[202:203]
	v_pk_mul_f32 v[26:27], v[26:27], v[128:129]
	v_pk_mul_f32 v[22:23], v[22:23], v[124:125]
	v_pk_mul_f32 v[32:33], v[32:33], v[204:205]
	v_pk_mul_f32 v[28:29], v[28:29], v[130:131]
	v_pk_mul_f32 v[24:25], v[24:25], v[126:127]
	v_pk_mul_f32 v[20:21], v[20:21], v[122:123]
	v_pk_mul_f32 v[18:19], v[18:19], v[120:121]
	v_pk_mul_f32 v[16:17], v[16:17], v[204:205]

.LBB0_680:
	s_and_b64 vcc, exec, s[2:3]
	s_barrier
	s_cbranch_vccnz .LBB0_682
	s_add_i32 m0, s89, 0x4000
	s_add_i32 s8, s89, s94
	global_load_lds_dwordx4 v134, s[52:53]
	s_add_i32 m0, s89, 0x4400
	s_nop 0
	global_load_lds_dwordx4 v154, s[52:53]
	s_add_i32 m0, s90, 0xa000
	s_add_u32 s52, s52, 0x40000
	s_addc_u32 s53, s53, 0
	global_load_lds_dwordx4 v144, s[54:55]
	s_add_i32 m0, s8, 0xc000
	s_add_u32 s54, s54, 0x100000
	s_addc_u32 s55, s55, 0
	global_load_lds_dwordx4 v142, s[48:49]
	s_add_i32 m0, s8, 0xc400
	s_nop 0
	global_load_lds_dwordx4 v152, s[48:49]
	s_add_u32 s48, s48, 0x40000
	s_addc_u32 s49, s49, 0

.LBB0_684:
	s_setprio 0
	v_max_f32_e32 v118, v83, v83
	v_max_f32_e32 v119, v82, v82
	v_max_f32_e32 v118, v119, v118
	v_max3_f32 v118, v118, v84, v85
	v_max3_f32 v118, v118, v86, v87
	v_max3_f32 v118, v118, v88, v89
	v_max3_f32 v118, v118, v90, v91
	v_max3_f32 v118, v118, v92, v93
	v_max3_f32 v118, v118, v94, v95
	v_max3_f32 v118, v118, v96, v97
	v_max3_f32 v118, v118, v66, v67
	v_max3_f32 v118, v118, v68, v69
	v_max3_f32 v118, v118, v70, v71
	v_max3_f32 v118, v118, v72, v73
	v_max3_f32 v118, v118, v74, v75
	v_max3_f32 v118, v118, v76, v77
	v_max3_f32 v118, v118, v78, v79
	v_max3_f32 v118, v118, v80, v81
	v_mov_b32_e32 v119, v118
	s_nop 1
	v_permlane32_swap_b32_e32 v118, v119
	v_max_f32_e32 v119, v119, v119
	v_max_f32_e32 v118, v118, v118
	v_max_f32_e32 v118, v118, v119
	v_max_f32_e32 v120, v186, v186
	v_sub_f32_e32 v119, v118, v186
	v_max_f32_e32 v118, v120, v118
	v_sub_f32_e32 v120, v186, v118
	v_exp_f32_e32 v120, v120
	v_cmp_ge_f32_e32 vcc, s80, v119
	s_cmp_eq_u64 vcc, exec
	s_cselect_b64 s[8:9], -1, 0
	v_cndmask_b32_e64 v204, v120, 1.0, s[8:9]
	v_cmp_gt_f32_e32 vcc, 1.0, v204
	s_cbranch_vccz .LBB0_688
	s_and_saveexec_b64 s[58:59], s[4:5]
	ds_write_b32 v157, v204 offset:128
	s_or_b64 exec, exec, s[58:59]
	s_waitcnt lgkmcnt(0)
	v_add_u32_e32 v119, s18, v156
	ds_read_b128 v[120:123], v119 offset:128
	ds_read_b128 v[124:127], v119 offset:160
	ds_read_b128 v[128:131], v119 offset:192
	ds_read_b128 v[206:209], v119 offset:224
	s_waitcnt lgkmcnt(0)
	v_pk_mul_f32 v[34:35], v[120:121], v[34:35]
	v_pk_mul_f32 v[36:37], v[36:37], v[122:123]
	v_pk_mul_f32 v[38:39], v[38:39], v[124:125]
	v_pk_mul_f32 v[40:41], v[40:41], v[126:127]
	v_pk_mul_f32 v[42:43], v[42:43], v[128:129]
	v_pk_mul_f32 v[44:45], v[44:45], v[130:131]
	v_pk_mul_f32 v[46:47], v[46:47], v[206:207]
	v_pk_mul_f32 v[62:63], v[62:63], v[206:207]
	v_pk_mul_f32 v[58:59], v[58:59], v[128:129]
	v_pk_mul_f32 v[54:55], v[54:55], v[124:125]
	v_pk_mul_f32 v[64:65], v[64:65], v[208:209]
	v_pk_mul_f32 v[60:61], v[60:61], v[130:131]
	v_pk_mul_f32 v[56:57], v[56:57], v[126:127]
	v_pk_mul_f32 v[52:53], v[52:53], v[122:123]
	v_pk_mul_f32 v[50:51], v[50:51], v[120:121]
	v_pk_mul_f32 v[48:49], v[48:49], v[208:209]
	v_pk_mul_f32 v[2:3], v[120:121], v[2:3]
	v_pk_mul_f32 v[4:5], v[4:5], v[122:123]
	v_pk_mul_f32 v[6:7], v[6:7], v[124:125]
	v_pk_mul_f32 v[8:9], v[8:9], v[126:127]
	v_pk_mul_f32 v[10:11], v[10:11], v[128:129]
	v_pk_mul_f32 v[12:13], v[12:13], v[130:131]
	v_pk_mul_f32 v[14:15], v[14:15], v[206:207]
	v_pk_mul_f32 v[30:31], v[30:31], v[206:207]
	v_pk_mul_f32 v[26:27], v[26:27], v[128:129]
	v_pk_mul_f32 v[22:23], v[22:23], v[124:125]
	v_pk_mul_f32 v[32:33], v[32:33], v[208:209]
	v_pk_mul_f32 v[28:29], v[28:29], v[130:131]
	v_pk_mul_f32 v[24:25], v[24:25], v[126:127]
	v_pk_mul_f32 v[20:21], v[20:21], v[122:123]
	v_pk_mul_f32 v[18:19], v[18:19], v[120:121]
	v_pk_mul_f32 v[16:17], v[16:17], v[208:209]
